# P5 epilogue in whole-line lane layout: x loaded and out stored 8 rows x 128 B per instruction, accumulator halves exchanged once by DPP under the load latency
# baseline (speedup 1.0000x reference)
;     __device__ __forceinline__ void operator()(const f32x4 (&acc)[2][2][4][2], const Unit& u, int wr, int wc, int fr, int fq) const {
;         const size_t row0 = (size_t)u.pm * BM + wr * 64 + fr; const int col0 = u.pn * BM + wc * 32 + 4 * fq; const float* gp = gate + (size_t)(u.pm >> 4) * 3072 + col0;
;         f32x4 gv[2][2];
; #pragma unroll
;         for (int bj = 0; bj < 2; ++bj)
; #pragma unroll
;             for (int n = 0; n < 2; ++n) gv[bj][n] = *(const f32x4*)(gp + bj * HALF + n * 16);
; #pragma unroll
;         for (int ai = 0; ai < 2; ++ai) {
;             f32x4 xv[4][2][2];
; #pragma unroll
;             for (int m = 0; m < 4; ++m) { const size_t off = (row0 + ai * HALF + m * 16) * 1024 + col0;
; #pragma unroll
;                 for (int bj = 0; bj < 2; ++bj)
; #pragma unroll
;                     for (int n = 0; n < 2; ++n) xv[m][bj][n] = *(const f32x4*)(x + off + bj * HALF + n * 16); }
;             asm volatile("" ::: "memory");
; #pragma unroll
;             for (int m = 0; m < 4; ++m) { const size_t off = (row0 + ai * HALF + m * 16) * 1024 + col0;
; #pragma unroll
;                 for (int bj = 0; bj < 2; ++bj)
; #pragma unroll
;                     for (int n = 0; n < 2; ++n) *(f32x4*)(out + off + bj * HALF + n * 16) = xv[m][bj][n] + gv[bj][n] * acc[ai][bj][m][n]; }
.LBB0_588:
	s_ashr_i32 s23, s30, 4
	s_ashr_i32 s31, s30, 31
	v_lshl_or_b32 v128, s61, 8, v163
	s_mul_hi_i32 s25, s23, 0x3000
	s_mulk_i32 s23, 0x3000
	s_add_u32 s34, s50, s23
	v_ashrrev_i32_e32 v129, 31, v128
	s_addc_u32 s35, s51, s25
	v_lshlrev_b64 v[232:233], 2, v[128:129]
	v_mbcnt_lo_u32_b32 v246, -1, 0
	v_mbcnt_hi_u32_b32 v246, -1, v246
	v_bfe_u32 v246, v246, 3, 1
	v_mul_i32_i24_e32 v246, 0xffff8040, v246
	v_ashrrev_i32_e32 v247, 31, v246
	v_lshl_add_u64 v[246:247], v[232:233], 0, v[246:247]
	v_mov_b32_e32 v248, 0x8000
	v_mov_b32_e32 v249, 0
	s_mov_b32 s88, 0xff00ff00
	s_mov_b32 s89, 0xff00ff00
	s_lshl_b64 s[30:31], s[30:31], 20
	v_lshl_add_u64 v[158:159], s[4:5], 0, v[246:247]
	v_lshl_add_u64 v[234:235], s[30:31], 0, v[148:149]
	v_lshl_add_u64 v[128:129], s[34:35], 0, v[232:233]
	v_lshl_add_u64 v[160:161], v[158:159], 0, v[234:235]
	global_load_dwordx4 v[168:171], v[160:161], off
	global_load_dwordx4 v[140:143], v[128:129], off
	global_load_dwordx4 v[136:139], v[128:129], off offset:64
	v_lshl_add_u64 v[250:251], v[160:161], 0, v[248:249]
	global_load_dwordx4 v[172:175], v[250:251], off
	global_load_dwordx4 v[176:179], v[160:161], off offset:512
	global_load_dwordx4 v[132:135], v[128:129], off offset:512
	s_nop 0
	global_load_dwordx4 v[128:131], v[128:129], off offset:576
	s_nop 0
	v_lshl_add_u64 v[252:253], v[160:161], 0, v[248:249]
	global_load_dwordx4 v[180:183], v[252:253], off offset:512
	v_or_b32_e32 v236, 0x10000, v234
	v_mov_b32_e32 v237, v235
	v_or_b32_e32 v238, 0x20000, v234
	v_mov_b32_e32 v239, v235
	v_or_b32_e32 v240, 0x30000, v234
	v_mov_b32_e32 v241, v235
	v_lshl_add_u64 v[196:197], v[158:159], 0, v[236:237]
	v_lshl_add_u64 v[212:213], v[158:159], 0, v[238:239]
	v_lshl_add_u64 v[158:159], v[158:159], 0, v[240:241]
	global_load_dwordx4 v[184:187], v[196:197], off
	v_lshl_add_u64 v[250:251], v[196:197], 0, v[248:249]
	global_load_dwordx4 v[188:191], v[250:251], off
	global_load_dwordx4 v[192:195], v[196:197], off offset:512
	s_nop 0
	v_lshl_add_u64 v[252:253], v[196:197], 0, v[248:249]
	global_load_dwordx4 v[196:199], v[252:253], off offset:512
	s_nop 0
	global_load_dwordx4 v[200:203], v[212:213], off
	v_lshl_add_u64 v[250:251], v[212:213], 0, v[248:249]
	global_load_dwordx4 v[204:207], v[250:251], off
	global_load_dwordx4 v[208:211], v[212:213], off offset:512
	s_nop 0
	v_lshl_add_u64 v[252:253], v[212:213], 0, v[248:249]
	global_load_dwordx4 v[212:215], v[252:253], off offset:512
	s_nop 0
	global_load_dwordx4 v[216:219], v[158:159], off
	v_lshl_add_u64 v[250:251], v[158:159], 0, v[248:249]
	global_load_dwordx4 v[220:223], v[250:251], off
	global_load_dwordx4 v[224:227], v[158:159], off offset:512
	v_lshl_add_u64 v[252:253], v[158:159], 0, v[248:249]
	global_load_dwordx4 v[228:231], v[252:253], off offset:512
	v_lshl_add_u64 v[158:159], s[6:7], 0, v[234:235]
	v_lshl_add_u64 v[158:159], v[158:159], 0, v[246:247]
	v_lshl_add_u64 v[234:235], s[6:7], 0, v[236:237]
	v_lshl_add_u64 v[236:237], s[6:7], 0, v[238:239]
	v_lshl_add_u64 v[238:239], s[6:7], 0, v[240:241]
	v_lshl_add_u64 v[234:235], v[234:235], 0, v[246:247]
	v_lshl_add_u64 v[236:237], v[236:237], 0, v[246:247]
	v_mov_b32_e32 v252, v124
	v_mov_b32_e32 v253, v125
	v_mov_b32_e32 v254, v126
	v_mov_b32_e32 v255, v127
	v_mov_b32_dpp v124, v120 row_shr:8 row_mask:0xf bank_mask:0xc
	v_mov_b32_dpp v125, v121 row_shr:8 row_mask:0xf bank_mask:0xc
	v_mov_b32_dpp v126, v122 row_shr:8 row_mask:0xf bank_mask:0xc
	v_mov_b32_dpp v127, v123 row_shr:8 row_mask:0xf bank_mask:0xc
	v_mov_b32_dpp v120, v252 row_shl:8 row_mask:0xf bank_mask:0x3
	v_mov_b32_dpp v121, v253 row_shl:8 row_mask:0xf bank_mask:0x3
	v_mov_b32_dpp v122, v254 row_shl:8 row_mask:0xf bank_mask:0x3
	v_mov_b32_dpp v123, v255 row_shl:8 row_mask:0xf bank_mask:0x3
	v_mov_b32_e32 v252, v104
	v_mov_b32_e32 v253, v105
	v_mov_b32_e32 v254, v106
	v_mov_b32_e32 v255, v107
	v_mov_b32_dpp v104, v96 row_shr:8 row_mask:0xf bank_mask:0xc
	v_mov_b32_dpp v105, v97 row_shr:8 row_mask:0xf bank_mask:0xc
	v_mov_b32_dpp v106, v98 row_shr:8 row_mask:0xf bank_mask:0xc
	v_mov_b32_dpp v107, v99 row_shr:8 row_mask:0xf bank_mask:0xc
	v_mov_b32_dpp v96, v252 row_shl:8 row_mask:0xf bank_mask:0x3
	v_mov_b32_dpp v97, v253 row_shl:8 row_mask:0xf bank_mask:0x3
	v_mov_b32_dpp v98, v254 row_shl:8 row_mask:0xf bank_mask:0x3
	v_mov_b32_dpp v99, v255 row_shl:8 row_mask:0xf bank_mask:0x3
	v_mov_b32_e32 v252, v116
	v_mov_b32_e32 v253, v117
	v_mov_b32_e32 v254, v118
	v_mov_b32_e32 v255, v119
	v_mov_b32_dpp v116, v112 row_shr:8 row_mask:0xf bank_mask:0xc
	v_mov_b32_dpp v117, v113 row_shr:8 row_mask:0xf bank_mask:0xc
	v_mov_b32_dpp v118, v114 row_shr:8 row_mask:0xf bank_mask:0xc
	v_mov_b32_dpp v119, v115 row_shr:8 row_mask:0xf bank_mask:0xc
	v_mov_b32_dpp v112, v252 row_shl:8 row_mask:0xf bank_mask:0x3
	v_mov_b32_dpp v113, v253 row_shl:8 row_mask:0xf bank_mask:0x3
	v_mov_b32_dpp v114, v254 row_shl:8 row_mask:0xf bank_mask:0x3
	v_mov_b32_dpp v115, v255 row_shl:8 row_mask:0xf bank_mask:0x3
	v_mov_b32_e32 v252, v88
	v_mov_b32_e32 v253, v89
	v_mov_b32_e32 v254, v90
	v_mov_b32_e32 v255, v91
	v_mov_b32_dpp v88, v84 row_shr:8 row_mask:0xf bank_mask:0xc
	v_mov_b32_dpp v89, v85 row_shr:8 row_mask:0xf bank_mask:0xc
	v_mov_b32_dpp v90, v86 row_shr:8 row_mask:0xf bank_mask:0xc
	v_mov_b32_dpp v91, v87 row_shr:8 row_mask:0xf bank_mask:0xc
	v_mov_b32_dpp v84, v252 row_shl:8 row_mask:0xf bank_mask:0x3
	v_mov_b32_dpp v85, v253 row_shl:8 row_mask:0xf bank_mask:0x3
	v_mov_b32_dpp v86, v254 row_shl:8 row_mask:0xf bank_mask:0x3
	v_mov_b32_dpp v87, v255 row_shl:8 row_mask:0xf bank_mask:0x3
	v_mov_b32_e32 v252, v108
	v_mov_b32_e32 v253, v109
	v_mov_b32_e32 v254, v110
	v_mov_b32_e32 v255, v111
;     __device__ __forceinline__ void operator()(const f32x4 (&acc)[2][2][4][2], const Unit& u, int wr, int wc, int fr, int fq) const {
;         const size_t row0 = (size_t)u.pm * BM + wr * 64 + fr; const int col0 = u.pn * BM + wc * 32 + 4 * fq; const float* gp = gate + (size_t)(u.pm >> 4) * 3072 + col0;
;         f32x4 gv[2][2];
; #pragma unroll
;         for (int bj = 0; bj < 2; ++bj)
; #pragma unroll
;             for (int n = 0; n < 2; ++n) gv[bj][n] = *(const f32x4*)(gp + bj * HALF + n * 16);
; #pragma unroll
;         for (int ai = 0; ai < 2; ++ai) {
;             f32x4 xv[4][2][2];
; #pragma unroll
;             for (int m = 0; m < 4; ++m) { const size_t off = (row0 + ai * HALF + m * 16) * 1024 + col0;
; #pragma unroll
;                 for (int bj = 0; bj < 2; ++bj)
; #pragma unroll
;                     for (int n = 0; n < 2; ++n) xv[m][bj][n] = *(const f32x4*)(x + off + bj * HALF + n * 16); }
;             asm volatile("" ::: "memory");
; #pragma unroll
;             for (int m = 0; m < 4; ++m) { const size_t off = (row0 + ai * HALF + m * 16) * 1024 + col0;
; #pragma unroll
;                 for (int bj = 0; bj < 2; ++bj)
; #pragma unroll
;                     for (int n = 0; n < 2; ++n) *(f32x4*)(out + off + bj * HALF + n * 16) = xv[m][bj][n] + gv[bj][n] * acc[ai][bj][m][n]; }
	v_mov_b32_dpp v108, v100 row_shr:8 row_mask:0xf bank_mask:0xc
	v_mov_b32_dpp v109, v101 row_shr:8 row_mask:0xf bank_mask:0xc
	v_mov_b32_dpp v110, v102 row_shr:8 row_mask:0xf bank_mask:0xc
	v_mov_b32_dpp v111, v103 row_shr:8 row_mask:0xf bank_mask:0xc
	v_mov_b32_dpp v100, v252 row_shl:8 row_mask:0xf bank_mask:0x3
	v_mov_b32_dpp v101, v253 row_shl:8 row_mask:0xf bank_mask:0x3
	v_mov_b32_dpp v102, v254 row_shl:8 row_mask:0xf bank_mask:0x3
	v_mov_b32_dpp v103, v255 row_shl:8 row_mask:0xf bank_mask:0x3
	v_mov_b32_e32 v252, v80
	v_mov_b32_e32 v253, v81
	v_mov_b32_e32 v254, v82
	v_mov_b32_e32 v255, v83
	v_mov_b32_dpp v80, v72 row_shr:8 row_mask:0xf bank_mask:0xc
	v_mov_b32_dpp v81, v73 row_shr:8 row_mask:0xf bank_mask:0xc
	v_mov_b32_dpp v82, v74 row_shr:8 row_mask:0xf bank_mask:0xc
	v_mov_b32_dpp v83, v75 row_shr:8 row_mask:0xf bank_mask:0xc
	v_mov_b32_dpp v72, v252 row_shl:8 row_mask:0xf bank_mask:0x3
	v_mov_b32_dpp v73, v253 row_shl:8 row_mask:0xf bank_mask:0x3
	v_mov_b32_dpp v74, v254 row_shl:8 row_mask:0xf bank_mask:0x3
	v_mov_b32_dpp v75, v255 row_shl:8 row_mask:0xf bank_mask:0x3
	v_mov_b32_e32 v252, v92
	v_mov_b32_e32 v253, v93
	v_mov_b32_e32 v254, v94
	v_mov_b32_e32 v255, v95
	v_mov_b32_dpp v92, v76 row_shr:8 row_mask:0xf bank_mask:0xc
	v_mov_b32_dpp v93, v77 row_shr:8 row_mask:0xf bank_mask:0xc
	v_mov_b32_dpp v94, v78 row_shr:8 row_mask:0xf bank_mask:0xc
	v_mov_b32_dpp v95, v79 row_shr:8 row_mask:0xf bank_mask:0xc
	v_mov_b32_dpp v76, v252 row_shl:8 row_mask:0xf bank_mask:0x3
	v_mov_b32_dpp v77, v253 row_shl:8 row_mask:0xf bank_mask:0x3
	v_mov_b32_dpp v78, v254 row_shl:8 row_mask:0xf bank_mask:0x3
	v_mov_b32_dpp v79, v255 row_shl:8 row_mask:0xf bank_mask:0x3
	v_mov_b32_e32 v252, v68
	v_mov_b32_e32 v253, v69
	v_mov_b32_e32 v254, v70
	v_mov_b32_e32 v255, v71
	v_mov_b32_dpp v68, v64 row_shr:8 row_mask:0xf bank_mask:0xc
	v_mov_b32_dpp v69, v65 row_shr:8 row_mask:0xf bank_mask:0xc
	v_mov_b32_dpp v70, v66 row_shr:8 row_mask:0xf bank_mask:0xc
	v_mov_b32_dpp v71, v67 row_shr:8 row_mask:0xf bank_mask:0xc
	v_mov_b32_dpp v64, v252 row_shl:8 row_mask:0xf bank_mask:0x3
	v_mov_b32_dpp v65, v253 row_shl:8 row_mask:0xf bank_mask:0x3
	v_mov_b32_dpp v66, v254 row_shl:8 row_mask:0xf bank_mask:0x3
	v_mov_b32_dpp v67, v255 row_shl:8 row_mask:0xf bank_mask:0x3
	v_mov_b32_e32 v252, v60
	v_mov_b32_e32 v253, v61
	v_mov_b32_e32 v254, v62
	v_mov_b32_e32 v255, v63
	v_mov_b32_dpp v60, v56 row_shr:8 row_mask:0xf bank_mask:0xc
	v_mov_b32_dpp v61, v57 row_shr:8 row_mask:0xf bank_mask:0xc
	v_mov_b32_dpp v62, v58 row_shr:8 row_mask:0xf bank_mask:0xc
	v_mov_b32_dpp v63, v59 row_shr:8 row_mask:0xf bank_mask:0xc
	v_mov_b32_dpp v56, v252 row_shl:8 row_mask:0xf bank_mask:0x3
	v_mov_b32_dpp v57, v253 row_shl:8 row_mask:0xf bank_mask:0x3
	v_mov_b32_dpp v58, v254 row_shl:8 row_mask:0xf bank_mask:0x3
	v_mov_b32_dpp v59, v255 row_shl:8 row_mask:0xf bank_mask:0x3
	v_mov_b32_e32 v252, v44
	v_mov_b32_e32 v253, v45
	v_mov_b32_e32 v254, v46
	v_mov_b32_e32 v255, v47
	v_mov_b32_dpp v44, v40 row_shr:8 row_mask:0xf bank_mask:0xc
	v_mov_b32_dpp v45, v41 row_shr:8 row_mask:0xf bank_mask:0xc
	v_mov_b32_dpp v46, v42 row_shr:8 row_mask:0xf bank_mask:0xc
	v_mov_b32_dpp v47, v43 row_shr:8 row_mask:0xf bank_mask:0xc
	v_mov_b32_dpp v40, v252 row_shl:8 row_mask:0xf bank_mask:0x3
	v_mov_b32_dpp v41, v253 row_shl:8 row_mask:0xf bank_mask:0x3
	v_mov_b32_dpp v42, v254 row_shl:8 row_mask:0xf bank_mask:0x3
	v_mov_b32_dpp v43, v255 row_shl:8 row_mask:0xf bank_mask:0x3
	v_mov_b32_e32 v252, v52
	v_mov_b32_e32 v253, v53
	v_mov_b32_e32 v254, v54
	v_mov_b32_e32 v255, v55
	v_mov_b32_dpp v52, v48 row_shr:8 row_mask:0xf bank_mask:0xc
	v_mov_b32_dpp v53, v49 row_shr:8 row_mask:0xf bank_mask:0xc
	v_mov_b32_dpp v54, v50 row_shr:8 row_mask:0xf bank_mask:0xc
	v_mov_b32_dpp v55, v51 row_shr:8 row_mask:0xf bank_mask:0xc
	v_mov_b32_dpp v48, v252 row_shl:8 row_mask:0xf bank_mask:0x3
	v_mov_b32_dpp v49, v253 row_shl:8 row_mask:0xf bank_mask:0x3
	v_mov_b32_dpp v50, v254 row_shl:8 row_mask:0xf bank_mask:0x3
	v_mov_b32_dpp v51, v255 row_shl:8 row_mask:0xf bank_mask:0x3
	v_mov_b32_e32 v252, v36
	v_mov_b32_e32 v253, v37
	v_mov_b32_e32 v254, v38
	v_mov_b32_e32 v255, v39
	v_mov_b32_dpp v36, v28 row_shr:8 row_mask:0xf bank_mask:0xc
	v_mov_b32_dpp v37, v29 row_shr:8 row_mask:0xf bank_mask:0xc
	v_mov_b32_dpp v38, v30 row_shr:8 row_mask:0xf bank_mask:0xc
	v_mov_b32_dpp v39, v31 row_shr:8 row_mask:0xf bank_mask:0xc
	v_mov_b32_dpp v28, v252 row_shl:8 row_mask:0xf bank_mask:0x3
	v_mov_b32_dpp v29, v253 row_shl:8 row_mask:0xf bank_mask:0x3
	v_mov_b32_dpp v30, v254 row_shl:8 row_mask:0xf bank_mask:0x3
	v_mov_b32_dpp v31, v255 row_shl:8 row_mask:0xf bank_mask:0x3
	v_mov_b32_e32 v252, v32
	v_mov_b32_e32 v253, v33
	v_mov_b32_e32 v254, v34
	v_mov_b32_e32 v255, v35
	v_mov_b32_dpp v32, v24 row_shr:8 row_mask:0xf bank_mask:0xc
	v_mov_b32_dpp v33, v25 row_shr:8 row_mask:0xf bank_mask:0xc
	v_mov_b32_dpp v34, v26 row_shr:8 row_mask:0xf bank_mask:0xc
	v_mov_b32_dpp v35, v27 row_shr:8 row_mask:0xf bank_mask:0xc
	v_mov_b32_dpp v24, v252 row_shl:8 row_mask:0xf bank_mask:0x3
	v_mov_b32_dpp v25, v253 row_shl:8 row_mask:0xf bank_mask:0x3
	v_mov_b32_dpp v26, v254 row_shl:8 row_mask:0xf bank_mask:0x3
	v_mov_b32_dpp v27, v255 row_shl:8 row_mask:0xf bank_mask:0x3
	v_mov_b32_e32 v252, v16
	v_mov_b32_e32 v253, v17
	v_mov_b32_e32 v254, v18
	v_mov_b32_e32 v255, v19
	v_mov_b32_dpp v16, v12 row_shr:8 row_mask:0xf bank_mask:0xc
	v_mov_b32_dpp v17, v13 row_shr:8 row_mask:0xf bank_mask:0xc
	v_mov_b32_dpp v18, v14 row_shr:8 row_mask:0xf bank_mask:0xc
	v_mov_b32_dpp v19, v15 row_shr:8 row_mask:0xf bank_mask:0xc
	v_mov_b32_dpp v12, v252 row_shl:8 row_mask:0xf bank_mask:0x3
	v_mov_b32_dpp v13, v253 row_shl:8 row_mask:0xf bank_mask:0x3
	v_mov_b32_dpp v14, v254 row_shl:8 row_mask:0xf bank_mask:0x3
	v_mov_b32_dpp v15, v255 row_shl:8 row_mask:0xf bank_mask:0x3
	v_mov_b32_e32 v252, v20
	v_mov_b32_e32 v253, v21
	v_mov_b32_e32 v254, v22
	v_mov_b32_e32 v255, v23
	v_mov_b32_dpp v20, v8 row_shr:8 row_mask:0xf bank_mask:0xc
	v_mov_b32_dpp v21, v9 row_shr:8 row_mask:0xf bank_mask:0xc
	v_mov_b32_dpp v22, v10 row_shr:8 row_mask:0xf bank_mask:0xc
	v_mov_b32_dpp v23, v11 row_shr:8 row_mask:0xf bank_mask:0xc
	v_mov_b32_dpp v8, v252 row_shl:8 row_mask:0xf bank_mask:0x3
	v_mov_b32_dpp v9, v253 row_shl:8 row_mask:0xf bank_mask:0x3
	v_mov_b32_dpp v10, v254 row_shl:8 row_mask:0xf bank_mask:0x3
	v_mov_b32_dpp v11, v255 row_shl:8 row_mask:0xf bank_mask:0x3
	v_mov_b32_e32 v252, v4
	v_mov_b32_e32 v253, v5
	v_mov_b32_e32 v254, v6
	v_mov_b32_e32 v255, v7
	v_mov_b32_dpp v4, v0 row_shr:8 row_mask:0xf bank_mask:0xc
	v_mov_b32_dpp v5, v1 row_shr:8 row_mask:0xf bank_mask:0xc
	v_mov_b32_dpp v6, v2 row_shr:8 row_mask:0xf bank_mask:0xc
	v_mov_b32_dpp v7, v3 row_shr:8 row_mask:0xf bank_mask:0xc
	v_mov_b32_dpp v0, v252 row_shl:8 row_mask:0xf bank_mask:0x3
	v_mov_b32_dpp v1, v253 row_shl:8 row_mask:0xf bank_mask:0x3
	v_mov_b32_dpp v2, v254 row_shl:8 row_mask:0xf bank_mask:0x3
	v_mov_b32_dpp v3, v255 row_shl:8 row_mask:0xf bank_mask:0x3
	s_waitcnt vmcnt(0)
;     __device__ __forceinline__ void operator()(const f32x4 (&acc)[2][2][4][2], const Unit& u, int wr, int wc, int fr, int fq) const {
;     ...
;             for (int n = 0; n < 2; ++n) gv[bj][n] = *(const f32x4*)(gp + bj * HALF + n * 16);
; #pragma unroll
;         for (int ai = 0; ai < 2; ++ai) {
;             f32x4 xv[4][2][2];
; #pragma unroll
;             for (int m = 0; m < 4; ++m) { const size_t off = (row0 + ai * HALF + m * 16) * 1024 + col0;
; #pragma unroll
;                 for (int bj = 0; bj < 2; ++bj)
; #pragma unroll
;                     for (int n = 0; n < 2; ++n) xv[m][bj][n] = *(const f32x4*)(x + off + bj * HALF + n * 16); }
;             asm volatile("" ::: "memory");
; #pragma unroll
;             for (int m = 0; m < 4; ++m) { const size_t off = (row0 + ai * HALF + m * 16) * 1024 + col0;
; #pragma unroll
;                 for (int bj = 0; bj < 2; ++bj)
; #pragma unroll
;                     for (int n = 0; n < 2; ++n) *(f32x4*)(out + off + bj * HALF + n * 16) = xv[m][bj][n] + gv[bj][n] * acc[ai][bj][m][n]; }
	v_cndmask_b32_e64 v140, v140, v136, s[88:89]
	v_cndmask_b32_e64 v141, v141, v137, s[88:89]
	v_cndmask_b32_e64 v142, v142, v138, s[88:89]
	v_cndmask_b32_e64 v143, v143, v139, s[88:89]
	v_cndmask_b32_e64 v132, v132, v128, s[88:89]
	v_cndmask_b32_e64 v133, v133, v129, s[88:89]
	v_cndmask_b32_e64 v134, v134, v130, s[88:89]
	v_cndmask_b32_e64 v135, v135, v131, s[88:89]
	v_pk_fma_f32 v[126:127], v[126:127], v[142:143], v[170:171]
	v_pk_fma_f32 v[124:125], v[124:125], v[140:141], v[168:169]
	v_pk_fma_f32 v[122:123], v[122:123], v[142:143], v[174:175]
	v_pk_fma_f32 v[120:121], v[120:121], v[140:141], v[172:173]
	v_pk_fma_f32 v[106:107], v[106:107], v[134:135], v[178:179]
	v_pk_fma_f32 v[104:105], v[104:105], v[132:133], v[176:177]
	v_pk_fma_f32 v[98:99], v[98:99], v[134:135], v[182:183]
	v_pk_fma_f32 v[96:97], v[96:97], v[132:133], v[180:181]
	v_lshl_add_u64 v[250:251], v[158:159], 0, v[248:249]
	global_store_dwordx4 v[158:159], v[124:127], off
	global_store_dwordx4 v[250:251], v[120:123], off
	v_lshl_add_u64 v[254:255], v[158:159], 0, v[248:249]
	global_store_dwordx4 v[158:159], v[104:107], off offset:512
	global_store_dwordx4 v[254:255], v[96:99], off offset:512
	v_lshl_add_u64 v[124:125], v[160:161], 0, s[20:21]
	v_lshl_add_u64 v[170:171], v[158:159], 0, s[16:17]
	v_pk_fma_f32 v[98:99], v[118:119], v[142:143], v[186:187]
	v_pk_fma_f32 v[96:97], v[116:117], v[140:141], v[184:185]
	v_pk_fma_f32 v[106:107], v[114:115], v[142:143], v[190:191]
	v_pk_fma_f32 v[80:81], v[80:81], v[132:133], v[208:209]
	v_pk_fma_f32 v[104:105], v[112:113], v[140:141], v[188:189]
	v_pk_fma_f32 v[90:91], v[90:91], v[134:135], v[194:195]
	v_pk_fma_f32 v[88:89], v[88:89], v[132:133], v[192:193]
	v_pk_fma_f32 v[86:87], v[86:87], v[134:135], v[198:199]
	v_pk_fma_f32 v[84:85], v[84:85], v[132:133], v[196:197]
	v_pk_fma_f32 v[110:111], v[110:111], v[142:143], v[202:203]
	v_pk_fma_f32 v[108:109], v[108:109], v[140:141], v[200:201]
	v_pk_fma_f32 v[102:103], v[102:103], v[142:143], v[206:207]
	v_pk_fma_f32 v[100:101], v[100:101], v[140:141], v[204:205]
	v_pk_fma_f32 v[82:83], v[82:83], v[134:135], v[210:211]
	v_pk_fma_f32 v[74:75], v[74:75], v[134:135], v[214:215]
	v_pk_fma_f32 v[72:73], v[72:73], v[132:133], v[212:213]
	v_lshl_add_u64 v[250:251], v[234:235], 0, v[248:249]
	global_store_dwordx4 v[234:235], v[96:99], off
	global_store_dwordx4 v[250:251], v[104:107], off
	v_lshl_add_u64 v[254:255], v[234:235], 0, v[248:249]
	global_store_dwordx4 v[234:235], v[88:91], off offset:512
	global_store_dwordx4 v[254:255], v[84:87], off offset:512
	v_lshl_add_u64 v[250:251], v[236:237], 0, v[248:249]
	global_store_dwordx4 v[236:237], v[108:111], off
	global_store_dwordx4 v[250:251], v[100:103], off
	v_lshl_add_u64 v[254:255], v[236:237], 0, v[248:249]
	global_store_dwordx4 v[236:237], v[80:83], off offset:512
	global_store_dwordx4 v[254:255], v[72:75], off offset:512
	v_pk_fma_f32 v[66:67], v[66:67], v[134:135], v[230:231]
	v_lshl_add_u64 v[80:81], v[238:239], 0, v[246:247]
	v_pk_fma_f32 v[64:65], v[64:65], v[132:133], v[228:229]
	v_pk_fma_f32 v[94:95], v[94:95], v[142:143], v[218:219]
	v_pk_fma_f32 v[92:93], v[92:93], v[140:141], v[216:217]
	v_add_co_u32_e32 v242, vcc, s57, v160
	v_pk_fma_f32 v[74:75], v[78:79], v[142:143], v[222:223]
	v_pk_fma_f32 v[72:73], v[76:77], v[140:141], v[220:221]
	v_pk_fma_f32 v[70:71], v[70:71], v[134:135], v[226:227]
	v_pk_fma_f32 v[68:69], v[68:69], v[132:133], v[224:225]
	v_addc_co_u32_e32 v243, vcc, 0, v161, vcc
	v_lshl_add_u64 v[250:251], v[80:81], 0, v[248:249]
	global_store_dwordx4 v[80:81], v[92:95], off
	global_store_dwordx4 v[250:251], v[72:75], off
	v_lshl_add_u64 v[254:255], v[80:81], 0, v[248:249]
	global_store_dwordx4 v[80:81], v[68:71], off offset:512
	global_store_dwordx4 v[254:255], v[64:67], off offset:512
	v_add_co_u32_e32 v80, vcc, s58, v160
	v_lshl_add_u64 v[76:77], v[160:161], 0, s[14:15]
	s_nop 0
	v_addc_co_u32_e32 v81, vcc, 0, v161, vcc
	v_lshl_add_u64 v[92:93], v[160:161], 0, s[16:17]
	v_add_co_u32_e32 v96, vcc, s59, v160
	global_load_dwordx4 v[64:67], v[242:243], off
	s_nop 0
	v_lshl_add_u64 v[250:251], v[76:77], 0, v[248:249]
	global_load_dwordx4 v[68:71], v[250:251], off
	global_load_dwordx4 v[72:75], v[76:77], off offset:512
	s_nop 0
	v_lshl_add_u64 v[252:253], v[76:77], 0, v[248:249]
	global_load_dwordx4 v[76:79], v[252:253], off offset:512
	v_addc_co_u32_e32 v97, vcc, 0, v161, vcc
	global_load_dwordx4 v[80:83], v[80:81], off
	s_nop 0
	v_lshl_add_u64 v[250:251], v[92:93], 0, v[248:249]
	global_load_dwordx4 v[84:87], v[250:251], off
	global_load_dwordx4 v[88:91], v[92:93], off offset:512
	s_nop 0
	v_lshl_add_u64 v[252:253], v[92:93], 0, v[248:249]
	global_load_dwordx4 v[92:95], v[252:253], off offset:512
	v_lshl_add_u64 v[108:109], v[160:161], 0, s[18:19]
	global_load_dwordx4 v[96:99], v[96:97], off
	v_add_co_u32_e32 v112, vcc, s60, v160
	v_lshl_add_u64 v[250:251], v[108:109], 0, v[248:249]
	global_load_dwordx4 v[100:103], v[250:251], off
	global_load_dwordx4 v[104:107], v[108:109], off offset:512
	s_nop 0
	v_lshl_add_u64 v[252:253], v[108:109], 0, v[248:249]
	global_load_dwordx4 v[108:111], v[252:253], off offset:512
	v_addc_co_u32_e32 v113, vcc, 0, v161, vcc
	global_load_dwordx4 v[112:115], v[112:113], off
	s_nop 0
	v_lshl_add_u64 v[250:251], v[124:125], 0, v[248:249]
	global_load_dwordx4 v[116:119], v[250:251], off
	global_load_dwordx4 v[120:123], v[124:125], off offset:512
	s_nop 0
	v_lshl_add_u64 v[252:253], v[124:125], 0, v[248:249]
	global_load_dwordx4 v[124:127], v[252:253], off offset:512
	v_lshl_add_u64 v[160:161], v[158:159], 0, s[14:15]
	s_nop 0
	s_waitcnt vmcnt(15)
;     __device__ __forceinline__ void operator()(const f32x4 (&acc)[2][2][4][2], const Unit& u, int wr, int wc, int fr, int fq) const {
;     ...
;             for (int m = 0; m < 4; ++m) { const size_t off = (row0 + ai * HALF + m * 16) * 1024 + col0;
; #pragma unroll
;                 for (int bj = 0; bj < 2; ++bj)
; #pragma unroll
;                     for (int n = 0; n < 2; ++n) xv[m][bj][n] = *(const f32x4*)(x + off + bj * HALF + n * 16); }
;             asm volatile("" ::: "memory");
; #pragma unroll
;             for (int m = 0; m < 4; ++m) { const size_t off = (row0 + ai * HALF + m * 16) * 1024 + col0;
; #pragma unroll
;                 for (int bj = 0; bj < 2; ++bj)
; #pragma unroll
;                     for (int n = 0; n < 2; ++n) *(f32x4*)(out + off + bj * HALF + n * 16) = xv[m][bj][n] + gv[bj][n] * acc[ai][bj][m][n]; }
;             asm volatile("" ::: "memory"); }
	v_pk_fma_f32 v[62:63], v[62:63], v[142:143], v[66:67]
	v_pk_fma_f32 v[60:61], v[60:61], v[140:141], v[64:65]
	s_waitcnt vmcnt(14)
	v_pk_fma_f32 v[58:59], v[58:59], v[142:143], v[70:71]
	v_pk_fma_f32 v[56:57], v[56:57], v[140:141], v[68:69]
	s_waitcnt vmcnt(13)
	v_pk_fma_f32 v[46:47], v[46:47], v[134:135], v[74:75]
	s_waitcnt vmcnt(8)
	v_pk_fma_f32 v[30:31], v[30:31], v[134:135], v[94:95]
	v_pk_fma_f32 v[44:45], v[44:45], v[132:133], v[72:73]
	v_pk_fma_f32 v[42:43], v[42:43], v[134:135], v[78:79]
	v_pk_fma_f32 v[40:41], v[40:41], v[132:133], v[76:77]
	v_pk_fma_f32 v[54:55], v[54:55], v[142:143], v[82:83]
	v_pk_fma_f32 v[52:53], v[52:53], v[140:141], v[80:81]
	v_pk_fma_f32 v[50:51], v[50:51], v[142:143], v[86:87]
	v_pk_fma_f32 v[48:49], v[48:49], v[140:141], v[84:85]
	v_pk_fma_f32 v[38:39], v[38:39], v[134:135], v[90:91]
	v_pk_fma_f32 v[36:37], v[36:37], v[132:133], v[88:89]
	v_pk_fma_f32 v[28:29], v[28:29], v[132:133], v[92:93]
	v_lshl_add_u64 v[250:251], v[160:161], 0, v[248:249]
	global_store_dwordx4 v[160:161], v[60:63], off
	global_store_dwordx4 v[250:251], v[56:59], off
	v_lshl_add_u64 v[254:255], v[160:161], 0, v[248:249]
	global_store_dwordx4 v[160:161], v[44:47], off offset:512
	global_store_dwordx4 v[254:255], v[40:43], off offset:512
	v_lshl_add_u64 v[250:251], v[170:171], 0, v[248:249]
	global_store_dwordx4 v[170:171], v[52:55], off
	global_store_dwordx4 v[250:251], v[48:51], off
	v_lshl_add_u64 v[254:255], v[170:171], 0, v[248:249]
	global_store_dwordx4 v[170:171], v[36:39], off offset:512
	global_store_dwordx4 v[254:255], v[28:31], off offset:512
	s_waitcnt vmcnt(13)
	v_pk_fma_f32 v[18:19], v[18:19], v[134:135], v[106:107]
	v_pk_fma_f32 v[16:17], v[16:17], v[132:133], v[104:105]
	v_pk_fma_f32 v[30:31], v[34:35], v[142:143], v[98:99]
	v_pk_fma_f32 v[28:29], v[32:33], v[140:141], v[96:97]
	v_lshl_add_u64 v[32:33], v[158:159], 0, s[18:19]
	s_waitcnt vmcnt(12)
	v_pk_fma_f32 v[14:15], v[14:15], v[134:135], v[110:111]
	v_pk_fma_f32 v[12:13], v[12:13], v[132:133], v[108:109]
	v_pk_fma_f32 v[26:27], v[26:27], v[142:143], v[102:103]
	v_pk_fma_f32 v[24:25], v[24:25], v[140:141], v[100:101]
	v_lshl_add_u64 v[254:255], v[32:33], 0, v[248:249]
	global_store_dwordx4 v[32:33], v[16:19], off offset:512
	global_store_dwordx4 v[254:255], v[12:15], off offset:512
	v_lshl_add_u64 v[244:245], v[158:159], 0, s[20:21]
	s_waitcnt vmcnt(13)
	v_pk_fma_f32 v[14:15], v[22:23], v[142:143], v[114:115]
	v_pk_fma_f32 v[12:13], v[20:21], v[140:141], v[112:113]
	s_waitcnt vmcnt(12)
	v_pk_fma_f32 v[10:11], v[10:11], v[142:143], v[118:119]
	v_pk_fma_f32 v[8:9], v[8:9], v[140:141], v[116:117]
	s_waitcnt vmcnt(11)
	v_pk_fma_f32 v[6:7], v[6:7], v[134:135], v[122:123]
	v_pk_fma_f32 v[4:5], v[4:5], v[132:133], v[120:121]
	s_waitcnt vmcnt(10)
	v_pk_fma_f32 v[2:3], v[2:3], v[134:135], v[126:127]
	v_pk_fma_f32 v[0:1], v[0:1], v[132:133], v[124:125]
	v_lshl_add_u64 v[250:251], v[32:33], 0, v[248:249]
	global_store_dwordx4 v[32:33], v[28:31], off
	global_store_dwordx4 v[250:251], v[24:27], off
	v_lshl_add_u64 v[250:251], v[244:245], 0, v[248:249]
	global_store_dwordx4 v[244:245], v[12:15], off
	global_store_dwordx4 v[250:251], v[8:11], off
	v_lshl_add_u64 v[254:255], v[244:245], 0, v[248:249]
	global_store_dwordx4 v[244:245], v[4:7], off offset:512
	global_store_dwordx4 v[254:255], v[0:3], off offset:512
	s_andn2_b64 vcc, exec, s[0:1]
	s_mov_b64 s[0:1], -1
	s_cbranch_vccnz .LBB0_577
	s_andn2_b64 vcc, exec, s[8:9]
	s_cbranch_vccnz .LBB0_576
	s_barrier
	s_branch .LBB0_576
